# attention 64-dim main loop unrolled by two with a second K/V prefetch register set: global loads issued two tiles ahead of their LDS staging
# baseline (speedup 1.0000x reference)
.Lstg_y_2:
	ds_read_b128 v[160:163], v199 offset:9216
	ds_read_b128 v[156:159], v199 offset:9248
	ds_read_b128 v[164:167], v199 offset:13824
	ds_read_b128 v[152:155], v199 offset:13856
	ds_read_b128 v[144:147], v199 offset:9280
	ds_read_b128 v[140:143], v199 offset:9312
	ds_read_b128 v[148:151], v199 offset:13888
	ds_read_b128 v[136:139], v199 offset:13920
	s_waitcnt lgkmcnt(14)
	v_mfma_f32_32x32x16_bf16 v[16:31], v[96:99], v[0:3], 0
	s_waitcnt vmcnt(1)
	ds_write_b128 v177, v[52:55]
	s_waitcnt vmcnt(0)
	ds_write2_b64 v215, v[48:49], v[50:51] offset1:2
	s_waitcnt lgkmcnt(14)
	v_mfma_f32_32x32x16_bf16 v[0:15], v[100:103], v[0:3], 0
	v_mfma_f32_32x32x16_bf16 v[16:31], v[68:71], v[104:107], v[16:31]
	v_mfma_f32_32x32x16_bf16 v[0:15], v[72:75], v[104:107], v[0:15]
	s_waitcnt lgkmcnt(13)
	v_mfma_f32_32x32x16_bf16 v[16:31], v[64:67], v[108:111], v[16:31]
	s_waitcnt lgkmcnt(11)
	v_mfma_f32_32x32x16_bf16 v[0:15], v[76:79], v[108:111], v[0:15]
	v_mfma_f32_32x32x16_bf16 v[16:31], v[60:63], v[112:115], v[16:31]
	s_waitcnt lgkmcnt(10)
	v_mfma_f32_32x32x16_bf16 v[0:15], v[56:59], v[112:115], v[0:15]
	global_load_dwordx4 v[104:107], v[190:191], off
	global_load_dwordx4 v[96:99], v[192:193], off
	v_lshl_add_u64 v[190:191], v[190:191], 0, s[20:21]
	v_lshl_add_u64 v[192:193], v[192:193], 0, s[22:23]
.LBB0_336:
	global_load_dwordx4 v[252:255], v[190:191], off
	global_load_dwordx4 v[236:239], v[192:193], off
	s_waitcnt lgkmcnt(2)
	v_mfma_f32_32x32x16_bf16 v[64:79], v[160:163], v[80:83], v[32:47]
	s_mov_b32 s8, s33
	v_mfma_f32_32x32x16_bf16 v[64:79], v[156:159], v[84:87], v[64:79]
	v_mfma_f32_32x32x16_bf16 v[64:79], v[144:147], v[92:95], v[64:79]
	v_mfma_f32_32x32x16_bf16 v[64:79], v[140:143], v[88:91], v[64:79]
	v_mfma_f32_32x32x16_bf16 v[48:63], v[164:167], v[80:83], v[32:47]
	s_and_b32 s33, 1, s76
	s_cselect_b32 s9, 0, 0x2400
	v_add_u32_e32 v100, s9, v199
	ds_read_b128 v[128:131], v100 offset:18432
	ds_read_b128 v[116:119], v100 offset:18464
	ds_read_b128 v[132:135], v100 offset:23040
	ds_read_b128 v[120:123], v100 offset:23072
	ds_read_b128 v[112:115], v100 offset:18496
	ds_read_b128 v[108:111], v100 offset:18528
	ds_read_b128 v[124:127], v100 offset:23104
	ds_read_b128 v[100:103], v100 offset:23136
	v_mfma_f32_32x32x16_bf16 v[48:63], v[152:155], v[84:87], v[48:63]
	v_exp_f32_e32 v64, v64
	v_exp_f32_e32 v65, v65
	v_exp_f32_e32 v66, v66
	v_mfma_f32_32x32x16_bf16 v[48:63], v[148:151], v[92:95], v[48:63]
	v_exp_f32_e32 v67, v67
	v_exp_f32_e32 v68, v68
	v_exp_f32_e32 v69, v69
	v_mfma_f32_32x32x16_bf16 v[48:63], v[136:139], v[88:91], v[48:63]
	v_exp_f32_e32 v70, v70
	v_exp_f32_e32 v71, v71
	v_exp_f32_e32 v72, v72
	v_exp_f32_e32 v73, v73
	v_exp_f32_e32 v74, v74
	v_exp_f32_e32 v75, v75
	v_exp_f32_e32 v76, v76
	v_exp_f32_e32 v77, v77
	v_exp_f32_e32 v78, v78
	v_exp_f32_e32 v79, v79
	s_setprio 0
	s_nop 0

.Lstg_y_4:
	s_mul_i32 s9, s77, 0x2400
	v_add_u32_e32 v235, s9, v199
	ds_read_b128 v[160:163], v235
	ds_read_b128 v[156:159], v235 offset:32
	ds_read_b128 v[164:167], v235 offset:4608
	ds_read_b128 v[152:155], v235 offset:4640
	ds_read_b128 v[144:147], v235 offset:64
	ds_read_b128 v[140:143], v235 offset:96
	ds_read_b128 v[148:151], v235 offset:4672
	ds_read_b128 v[136:139], v235 offset:4704
	s_waitcnt lgkmcnt(14)
	v_mfma_f32_32x32x16_bf16 v[16:31], v[128:131], v[48:51], v[16:31]
	v_add_f32_e32 v64, v64, v219
	v_add_f32_e32 v65, v65, v220
	v_add_f32_e32 v66, v66, v221
	v_add_f32_e32 v67, v67, v222
	v_add_f32_e32 v68, v68, v223
	s_mul_i32 s9, s8, 0x2400
	s_cmp_eq_u32 s33, 1
	s_cselect_b32 s18, 0, 0x2400
	s_add_i32 s76, s76, 1
	v_lshl_add_u64 v[190:191], v[190:191], 0, s[20:21]
	v_lshl_add_u64 v[192:193], v[192:193], 0, s[22:23]
	s_cmp_eq_u32 s76, 31
	s_waitcnt lgkmcnt(13)
	v_mfma_f32_32x32x16_bf16 v[0:15], v[132:135], v[48:51], v[0:15]
	v_add_f32_e32 v69, v69, v224
	v_add_f32_e32 v70, v70, v225
	v_add_f32_e32 v71, v71, v226
	v_add_f32_e32 v72, v72, v227
	v_add_f32_e32 v73, v73, v228
	v_add_u32_e32 v48, s9, v177
	s_waitcnt vmcnt(3)
	ds_write_b128 v48, v[104:107]
	v_add_u32_e32 v48, s18, v198
	v_add_u32_e32 v48, 0x4800, v48
	s_waitcnt vmcnt(2)
	ds_write2_b64 v48, v[96:97], v[98:99] offset1:2
	v_mfma_f32_32x32x16_bf16 v[16:31], v[116:119], v[52:55], v[16:31]
	v_add_f32_e32 v74, v74, v229
	v_add_f32_e32 v75, v75, v230
	v_add_f32_e32 v76, v76, v231
	v_add_f32_e32 v77, v77, v232
	v_add_f32_e32 v78, v78, v233
	s_waitcnt lgkmcnt(14)
	v_mfma_f32_32x32x16_bf16 v[0:15], v[120:123], v[52:55], v[0:15]
	v_add_f32_e32 v79, v79, v234
	v_add_f32_e32 v64, v64, v65
	v_add_f32_e32 v66, v66, v67
	v_add_f32_e32 v68, v68, v69
	v_add_f32_e32 v70, v70, v71
	s_waitcnt lgkmcnt(13)
	v_mfma_f32_32x32x16_bf16 v[16:31], v[112:115], v[56:59], v[16:31]
	v_add_f32_e32 v72, v72, v73
	v_add_f32_e32 v74, v74, v75
	v_add_f32_e32 v76, v76, v77
	v_add_f32_e32 v78, v78, v79
	s_waitcnt lgkmcnt(11)
	v_mfma_f32_32x32x16_bf16 v[0:15], v[124:127], v[56:59], v[0:15]
	v_add_f32_e32 v64, v64, v66
	v_add_f32_e32 v68, v68, v70
	v_add_f32_e32 v72, v72, v74
	v_add_f32_e32 v76, v76, v78
	v_mfma_f32_32x32x16_bf16 v[16:31], v[108:111], v[60:63], v[16:31]
	v_add_f32_e32 v64, v64, v68
	v_add_f32_e32 v72, v72, v76
	v_add_f32_e32 v64, v64, v72
	v_add_f32_e32 v194, v194, v64
	s_waitcnt lgkmcnt(10)
	v_mfma_f32_32x32x16_bf16 v[0:15], v[100:103], v[60:63], v[0:15]
	s_cbranch_scc1 .LBB0_340
	s_mov_b32 s33, s77
	s_mov_b32 s77, s8
.Lgq_even:
	global_load_dwordx4 v[104:107], v[190:191], off
	global_load_dwordx4 v[96:99], v[192:193], off
	s_waitcnt lgkmcnt(2)
	v_mfma_f32_32x32x16_bf16 v[64:79], v[160:163], v[80:83], v[32:47]
	s_mov_b32 s8, s33
	v_mfma_f32_32x32x16_bf16 v[64:79], v[156:159], v[84:87], v[64:79]
	v_mfma_f32_32x32x16_bf16 v[64:79], v[144:147], v[92:95], v[64:79]
	v_mfma_f32_32x32x16_bf16 v[64:79], v[140:143], v[88:91], v[64:79]
	v_mfma_f32_32x32x16_bf16 v[48:63], v[164:167], v[80:83], v[32:47]
	s_and_b32 s33, 1, s76
	s_cselect_b32 s9, 0, 0x2400
	v_add_u32_e32 v100, s9, v199
	ds_read_b128 v[128:131], v100 offset:18432
	ds_read_b128 v[116:119], v100 offset:18464
	ds_read_b128 v[132:135], v100 offset:23040
	ds_read_b128 v[120:123], v100 offset:23072
	ds_read_b128 v[112:115], v100 offset:18496
	ds_read_b128 v[108:111], v100 offset:18528
	ds_read_b128 v[124:127], v100 offset:23104
	ds_read_b128 v[100:103], v100 offset:23136
	v_mfma_f32_32x32x16_bf16 v[48:63], v[152:155], v[84:87], v[48:63]
	v_exp_f32_e32 v64, v64
	v_exp_f32_e32 v65, v65
	v_exp_f32_e32 v66, v66
	v_mfma_f32_32x32x16_bf16 v[48:63], v[148:151], v[92:95], v[48:63]
	v_exp_f32_e32 v67, v67
	v_exp_f32_e32 v68, v68
	v_exp_f32_e32 v69, v69
	v_mfma_f32_32x32x16_bf16 v[48:63], v[136:139], v[88:91], v[48:63]
	v_exp_f32_e32 v70, v70
	v_exp_f32_e32 v71, v71
	v_exp_f32_e32 v72, v72
	v_exp_f32_e32 v73, v73
	v_exp_f32_e32 v74, v74
	v_exp_f32_e32 v75, v75
	v_exp_f32_e32 v76, v76
	v_exp_f32_e32 v77, v77
	v_exp_f32_e32 v78, v78
	v_exp_f32_e32 v79, v79
	s_setprio 0
	s_nop 0
	v_exp_f32_e32 v219, v48
	v_exp_f32_e32 v220, v49
	v_exp_f32_e32 v221, v50
	v_exp_f32_e32 v222, v51
	v_exp_f32_e32 v223, v52
	v_exp_f32_e32 v224, v53
	v_exp_f32_e32 v225, v54
	v_exp_f32_e32 v226, v55
	s_cmp_eq_u32 s98, 0
	s_cbranch_scc1 .Lstg_x_3b
	s_waitcnt lgkmcnt(0)
	s_barrier

.Lstg_y_4b:
	s_mul_i32 s9, s77, 0x2400
	v_add_u32_e32 v235, s9, v199
	ds_read_b128 v[160:163], v235
	ds_read_b128 v[156:159], v235 offset:32
	ds_read_b128 v[164:167], v235 offset:4608
	ds_read_b128 v[152:155], v235 offset:4640
	ds_read_b128 v[144:147], v235 offset:64
	ds_read_b128 v[140:143], v235 offset:96
	ds_read_b128 v[148:151], v235 offset:4672
	ds_read_b128 v[136:139], v235 offset:4704
	s_waitcnt lgkmcnt(14)
	v_mfma_f32_32x32x16_bf16 v[16:31], v[128:131], v[48:51], v[16:31]
	v_add_f32_e32 v64, v64, v219
	v_add_f32_e32 v65, v65, v220
	v_add_f32_e32 v66, v66, v221
	v_add_f32_e32 v67, v67, v222
	v_add_f32_e32 v68, v68, v223
	s_mul_i32 s9, s8, 0x2400
	s_cmp_eq_u32 s33, 1
	s_cselect_b32 s18, 0, 0x2400
	s_add_i32 s76, s76, 1
	v_lshl_add_u64 v[190:191], v[190:191], 0, s[20:21]
	v_lshl_add_u64 v[192:193], v[192:193], 0, s[22:23]
	s_cmp_eq_u32 s76, 31
	s_waitcnt lgkmcnt(13)
	v_mfma_f32_32x32x16_bf16 v[0:15], v[132:135], v[48:51], v[0:15]
	v_add_f32_e32 v69, v69, v224
	v_add_f32_e32 v70, v70, v225
	v_add_f32_e32 v71, v71, v226
	v_add_f32_e32 v72, v72, v227
	v_add_f32_e32 v73, v73, v228
	v_add_u32_e32 v48, s9, v177
	s_waitcnt vmcnt(3)
	ds_write_b128 v48, v[252:255]
	v_add_u32_e32 v48, s18, v198
	v_add_u32_e32 v48, 0x4800, v48
	s_waitcnt vmcnt(2)
	ds_write2_b64 v48, v[236:237], v[238:239] offset1:2
	v_mfma_f32_32x32x16_bf16 v[16:31], v[116:119], v[52:55], v[16:31]
	v_add_f32_e32 v74, v74, v229
	v_add_f32_e32 v75, v75, v230
	v_add_f32_e32 v76, v76, v231
	v_add_f32_e32 v77, v77, v232
	v_add_f32_e32 v78, v78, v233
	s_waitcnt lgkmcnt(14)
	v_mfma_f32_32x32x16_bf16 v[0:15], v[120:123], v[52:55], v[0:15]
	v_add_f32_e32 v79, v79, v234
	v_add_f32_e32 v64, v64, v65
	v_add_f32_e32 v66, v66, v67
	v_add_f32_e32 v68, v68, v69
	v_add_f32_e32 v70, v70, v71
	s_waitcnt lgkmcnt(13)
	v_mfma_f32_32x32x16_bf16 v[16:31], v[112:115], v[56:59], v[16:31]
	v_add_f32_e32 v72, v72, v73
	v_add_f32_e32 v74, v74, v75
	v_add_f32_e32 v76, v76, v77
	v_add_f32_e32 v78, v78, v79
	s_waitcnt lgkmcnt(11)
	v_mfma_f32_32x32x16_bf16 v[0:15], v[124:127], v[56:59], v[0:15]
	v_add_f32_e32 v64, v64, v66
	v_add_f32_e32 v68, v68, v70
	v_add_f32_e32 v72, v72, v74
	v_add_f32_e32 v76, v76, v78
	v_mfma_f32_32x32x16_bf16 v[16:31], v[108:111], v[60:63], v[16:31]
	v_add_f32_e32 v64, v64, v68
	v_add_f32_e32 v72, v72, v76
	v_add_f32_e32 v64, v64, v72
	v_add_f32_e32 v194, v194, v64
	s_waitcnt lgkmcnt(10)
	v_mfma_f32_32x32x16_bf16 v[0:15], v[100:103], v[60:63], v[0:15]
	s_cbranch_scc1 .LBB0_340
	s_mov_b32 s33, s77
	s_mov_b32 s77, s8
	s_branch .LBB0_336

	.amdhsa_kernel _Z10fwd_kernel4Args
		.amdhsa_group_segment_fixed_size 0
		.amdhsa_private_segment_fixed_size 0
		.amdhsa_kernarg_size 424
		.amdhsa_user_sgpr_count 2
		.amdhsa_user_sgpr_dispatch_ptr 0
		.amdhsa_user_sgpr_queue_ptr 0
		.amdhsa_user_sgpr_kernarg_segment_ptr 1
		.amdhsa_user_sgpr_dispatch_id 0
		.amdhsa_user_sgpr_kernarg_preload_length 0
		.amdhsa_user_sgpr_kernarg_preload_offset 0
		.amdhsa_user_sgpr_private_segment_size 0
		.amdhsa_uses_dynamic_stack 0
		.amdhsa_enable_private_segment 0
		.amdhsa_system_sgpr_workgroup_id_x 1
		.amdhsa_system_sgpr_workgroup_id_y 0
		.amdhsa_system_sgpr_workgroup_id_z 0
		.amdhsa_system_sgpr_workgroup_info 0
		.amdhsa_system_vgpr_workitem_id 2
		.amdhsa_next_free_vgpr 256
		.amdhsa_next_free_sgpr 101
		.amdhsa_accum_offset 256
		.amdhsa_reserve_vcc 1
		.amdhsa_float_round_mode_32 0
		.amdhsa_float_round_mode_16_64 0
		.amdhsa_float_denorm_mode_32 3
		.amdhsa_float_denorm_mode_16_64 3
		.amdhsa_dx10_clamp 1
		.amdhsa_ieee_mode 1
		.amdhsa_fp16_overflow 0
		.amdhsa_tg_split 0
		.amdhsa_exception_fp_ieee_invalid_op 0
		.amdhsa_exception_fp_denorm_src 0
		.amdhsa_exception_fp_ieee_div_zero 0
		.amdhsa_exception_fp_ieee_overflow 0
		.amdhsa_exception_fp_ieee_underflow 0
		.amdhsa_exception_fp_ieee_inexact 0
		.amdhsa_exception_int_div_zero 0
	.end_amdhsa_kernel

amdhsa.kernels:
  - .agpr_count:     0
    .args:
      - .offset:         0
        .size:           168
        .value_kind:     by_value
      - .offset:         168
        .size:           4
        .value_kind:     hidden_block_count_x
      - .offset:         172
        .size:           4
        .value_kind:     hidden_block_count_y
      - .offset:         176
        .size:           4
        .value_kind:     hidden_block_count_z
      - .offset:         180
        .size:           2
        .value_kind:     hidden_group_size_x
      - .offset:         182
        .size:           2
        .value_kind:     hidden_group_size_y
      - .offset:         184
        .size:           2
        .value_kind:     hidden_group_size_z
      - .offset:         186
        .size:           2
        .value_kind:     hidden_remainder_x
      - .offset:         188
        .size:           2
        .value_kind:     hidden_remainder_y
      - .offset:         190
        .size:           2
        .value_kind:     hidden_remainder_z
      - .offset:         208
        .size:           8
        .value_kind:     hidden_global_offset_x
      - .offset:         216
        .size:           8
        .value_kind:     hidden_global_offset_y
      - .offset:         224
        .size:           8
        .value_kind:     hidden_global_offset_z
      - .offset:         232
        .size:           2
        .value_kind:     hidden_grid_dims
      - .offset:         256
        .size:           8
        .value_kind:     hidden_multigrid_sync_arg
      - .offset:         288
        .size:           4
        .value_kind:     hidden_dynamic_lds_size
    .group_segment_fixed_size: 0
    .kernarg_segment_align: 8
    .kernarg_segment_size: 424
    .language:       OpenCL C
    .language_version:
      - 2
      - 0
    .max_flat_workgroup_size: 512
    .name:           _Z10fwd_kernel4Args
    .private_segment_fixed_size: 0
    .sgpr_count:     107
    .sgpr_spill_count: 52
    .symbol:         _Z10fwd_kernel4Args.kd
    .uniform_work_group_size: 1
    .uses_dynamic_stack: false
    .vgpr_count:     256
    .vgpr_spill_count: 0
    .wavefront_size: 64
